# mini_ring main loop rotated (in-proj x2, FFN-down): fragment reads issued right after the chunk barrier, next-chunk LDS-DMA (7 ahead) and loop bookkeeping overlap the LDS latency
# speedup vs baseline: 1.0004x; 1.0004x over previous
; #define MR_ISSUE(c) do { const unsigned sb_ = ldw + (unsigned)(((c) & (NS - 1)) * SLOT); glds16_m(src[0] + (size_t)(c) * 128, sb_); glds16_m(src[1] + (size_t)(c) * 128, sb_ + 8192u); } while (0)
; template <class Epi>
; __device__ __forceinline__ void mini_ring(PG8_LAS unsigned char* lds, const bf16_t* A, const bf16_t* Bt, int K, const Epi& E, int mu, int wave_u) {
;     ...
; #pragma unroll
;     for (int c = 0; c < PD; ++c) MR_ISSUE(c);
;     f32x4 acc[2][2];
; #pragma unroll
;     for (int b = 0; b < 2; ++b)
; #pragma unroll
;         for (int n = 0; n < 2; ++n) acc[b][n] = (f32x4){0.f, 0.f, 0.f, 0.f};
;     const int x0 = ((fq) ^ (fr & 7)) * 16, x1 = ((4 + fq) ^ (fr & 7)) * 16;
;     const int aoff = (16 * (w & 3) + fr) * 128;
;     ...
;     const int nmain = nchunk - PD;
; #pragma unroll 1
;     for (int c = 0; c < nmain; ++c) {
;         MR_ISSUE(c + PD);
;         asm volatile("s_waitcnt vmcnt(12)" ::: "memory"); __builtin_amdgcn_s_barrier(); asm volatile("" ::: "memory");
;         MR_CONSUME(c);
;     }
.LBB0_201:
	s_add_i32 s24, s0, 0x18000
	s_mov_b32 m0, s24
	s_nop 0
	global_load_lds_dwordx4 v[22:23], off
	s_addk_i32 s24, 0x2000
	s_mov_b32 m0, s24
	s_nop 0
	global_load_lds_dwordx4 v[20:21], off
	v_lshl_add_u64 v[20:21], v[20:21], 0, s[38:39]
	v_lshl_add_u64 v[22:23], v[22:23], 0, s[38:39]
	v_cndmask_b32_e64 v0, 0, 1, s[16:17]
	v_cmp_ne_u32_e64 s[10:11], 1, v0
.Lmr_a_head:
	s_waitcnt vmcnt(12)
	s_barrier
	s_andn2_b64 vcc, exec, s[16:17]
	s_cbranch_vccnz .Lmr_a_issue
	s_and_b32 s24, s1, 0x1c000
	v_add_u32_e32 v0, s24, v28
	v_add_u32_e32 v29, v0, v26
	v_add_u32_e32 v2, s24, v27
	v_add_u32_e32 v3, v2, v26
	v_add_u32_e32 v0, v0, v25
	v_add_u32_e32 v2, v2, v25
	ds_read_b128 v[34:37], v3
	ds_read_b128 v[30:33], v29 offset:8192
	ds_read_b128 v[44:47], v29 offset:10240
	ds_read_b128 v[48:51], v29 offset:12288
	ds_read_b128 v[56:59], v29 offset:14336
	ds_read_b128 v[38:41], v2
	ds_read_b128 v[64:67], v0 offset:8192
	ds_read_b128 v[68:71], v0 offset:10240
.Lmr_a_issue:
	s_cmp_eq_u32 s1, 0x24000
	s_cbranch_scc1 .Lmr_a_nodma
	s_add_i32 s24, s1, 0x1c000
	s_and_b32 s24, s24, 0x1c000
	s_add_i32 s24, s24, s0
	s_mov_b32 m0, s24
	s_nop 0
	global_load_lds_dwordx4 v[22:23], off
	s_addk_i32 s24, 0x2000
	s_mov_b32 m0, s24
	s_nop 0
	global_load_lds_dwordx4 v[20:21], off
	v_lshl_add_u64 v[20:21], v[20:21], 0, s[38:39]
	v_lshl_add_u64 v[22:23], v[22:23], 0, s[38:39]
.Lmr_a_nodma:
	s_addk_i32 s1, 0x4000
	s_cbranch_vccnz .Lmr_a_tail
	s_waitcnt lgkmcnt(6)
	v_mfma_f32_16x16x32_bf16 v[16:19], v[30:33], v[34:37], v[16:19]
	ds_read_b128 v[30:33], v0 offset:12288
	s_waitcnt lgkmcnt(6)
	v_mfma_f32_16x16x32_bf16 v[12:15], v[44:47], v[34:37], v[12:15]
	ds_read_b128 v[44:47], v0 offset:14336
	s_waitcnt lgkmcnt(6)
	v_mfma_f32_16x16x32_bf16 v[4:7], v[48:51], v[34:37], v[4:7]
	s_waitcnt lgkmcnt(5)
	v_mfma_f32_16x16x32_bf16 v[8:11], v[56:59], v[34:37], v[8:11]
	s_waitcnt lgkmcnt(3)
	v_mfma_f32_16x16x32_bf16 v[16:19], v[64:67], v[38:41], v[16:19]
	s_waitcnt lgkmcnt(2)
	v_mfma_f32_16x16x32_bf16 v[12:15], v[68:71], v[38:41], v[12:15]
	s_waitcnt lgkmcnt(1)
	v_mfma_f32_16x16x32_bf16 v[4:7], v[30:33], v[38:41], v[4:7]
	s_waitcnt lgkmcnt(0)
	v_mfma_f32_16x16x32_bf16 v[8:11], v[44:47], v[38:41], v[8:11]
.Lmr_a_tail:
	s_cmp_eq_u32 s1, 0x28000
	s_cbranch_scc0 .Lmr_a_head

; #define MR_ISSUE(c) do { const unsigned sb_ = ldw + (unsigned)(((c) & (NS - 1)) * SLOT); glds16_m(src[0] + (size_t)(c) * 128, sb_); glds16_m(src[1] + (size_t)(c) * 128, sb_ + 8192u); } while (0)
; template <class Epi>
; __device__ __forceinline__ void mini_ring(PG8_LAS unsigned char* lds, const bf16_t* A, const bf16_t* Bt, int K, const Epi& E, int mu, int wave_u) {
;     ...
; #pragma unroll
;     for (int c = 0; c < PD; ++c) MR_ISSUE(c);
;     f32x4 acc[2][2];
; #pragma unroll
;     for (int b = 0; b < 2; ++b)
; #pragma unroll
;         for (int n = 0; n < 2; ++n) acc[b][n] = (f32x4){0.f, 0.f, 0.f, 0.f};
;     const int x0 = ((fq) ^ (fr & 7)) * 16, x1 = ((4 + fq) ^ (fr & 7)) * 16;
;     const int aoff = (16 * (w & 3) + fr) * 128;
;     ...
;     const int nmain = nchunk - PD;
; #pragma unroll 1
;     for (int c = 0; c < nmain; ++c) {
;         MR_ISSUE(c + PD);
;         asm volatile("s_waitcnt vmcnt(12)" ::: "memory"); __builtin_amdgcn_s_barrier(); asm volatile("" ::: "memory");
;         MR_CONSUME(c);
;     }
.LBB0_351:
	s_add_i32 s23, s0, 0x18000
	s_mov_b32 m0, s23
	s_nop 0
	global_load_lds_dwordx4 v[14:15], off
	s_addk_i32 s23, 0x2000
	s_mov_b32 m0, s23
	s_nop 0
	global_load_lds_dwordx4 v[12:13], off
	v_lshl_add_u64 v[12:13], v[12:13], 0, s[38:39]
	v_lshl_add_u64 v[14:15], v[14:15], 0, s[38:39]
	v_cndmask_b32_e64 v0, 0, 1, s[14:15]
	v_cmp_ne_u32_e64 s[10:11], 1, v0
.Lmr_b_head:
	s_waitcnt vmcnt(12)
	s_barrier
	s_andn2_b64 vcc, exec, s[14:15]
	s_cbranch_vccnz .Lmr_b_issue
	s_and_b32 s23, s1, 0x1c000
	v_add_u32_e32 v0, s23, v20
	v_add_u32_e32 v21, v0, v18
	v_add_u32_e32 v2, s23, v19
	v_add_u32_e32 v3, v2, v18
	v_add_u32_e32 v0, v0, v17
	v_add_u32_e32 v2, v2, v17
	ds_read_b128 v[32:35], v3
	ds_read_b128 v[22:25], v21 offset:8192
	ds_read_b128 v[40:43], v21 offset:10240
	ds_read_b128 v[44:47], v21 offset:12288
	ds_read_b128 v[64:67], v21 offset:14336
	ds_read_b128 v[36:39], v2
.Lmr_b_issue:
	s_cmp_eq_u32 s1, 0x24000
	s_cbranch_scc1 .Lmr_b_nodma
	s_add_i32 s23, s1, 0x1c000
	s_and_b32 s23, s23, 0x1c000
	s_add_i32 s23, s23, s0
	s_mov_b32 m0, s23
	s_nop 0
	global_load_lds_dwordx4 v[14:15], off
	s_addk_i32 s23, 0x2000
	s_mov_b32 m0, s23
	s_nop 0
	global_load_lds_dwordx4 v[12:13], off
	v_lshl_add_u64 v[12:13], v[12:13], 0, s[38:39]
	v_lshl_add_u64 v[14:15], v[14:15], 0, s[38:39]
.Lmr_b_nodma:
	s_addk_i32 s1, 0x4000
	s_cbranch_vccnz .Lmr_b_tail
	s_waitcnt lgkmcnt(4)
	v_mfma_f32_16x16x32_bf16 v[48:51], v[22:25], v[32:35], v[48:51]
	ds_read_b128 v[22:25], v0 offset:8192
	s_waitcnt lgkmcnt(4)
	v_mfma_f32_16x16x32_bf16 v[28:31], v[40:43], v[32:35], v[28:31]
	ds_read_b128 v[40:43], v0 offset:10240
	s_waitcnt lgkmcnt(4)
	v_mfma_f32_16x16x32_bf16 v[4:7], v[44:47], v[32:35], v[4:7]
	ds_read_b128 v[44:47], v0 offset:12288
	s_waitcnt lgkmcnt(4)
	v_mfma_f32_16x16x32_bf16 v[8:11], v[64:67], v[32:35], v[8:11]
	ds_read_b128 v[64:67], v0 offset:14336
	s_waitcnt lgkmcnt(3)
	v_mfma_f32_16x16x32_bf16 v[48:51], v[22:25], v[36:39], v[48:51]
	s_waitcnt lgkmcnt(2)
	v_mfma_f32_16x16x32_bf16 v[28:31], v[40:43], v[36:39], v[28:31]
	s_waitcnt lgkmcnt(1)
	v_mfma_f32_16x16x32_bf16 v[4:7], v[44:47], v[36:39], v[4:7]
	s_waitcnt lgkmcnt(0)
	v_mfma_f32_16x16x32_bf16 v[8:11], v[64:67], v[36:39], v[8:11]

; #define MR_ISSUE(c) do { const unsigned sb_ = ldw + (unsigned)(((c) & (NS - 1)) * SLOT); glds16_m(src[0] + (size_t)(c) * 128, sb_); glds16_m(src[1] + (size_t)(c) * 128, sb_ + 8192u); } while (0)
; template <class Epi>
; __device__ __forceinline__ void mini_ring(PG8_LAS unsigned char* lds, const bf16_t* A, const bf16_t* Bt, int K, const Epi& E, int mu, int wave_u) {
;     ...
; #pragma unroll
;     for (int c = 0; c < PD; ++c) MR_ISSUE(c);
;     f32x4 acc[2][2];
; #pragma unroll
;     for (int b = 0; b < 2; ++b)
; #pragma unroll
;         for (int n = 0; n < 2; ++n) acc[b][n] = (f32x4){0.f, 0.f, 0.f, 0.f};
;     const int x0 = ((fq) ^ (fr & 7)) * 16, x1 = ((4 + fq) ^ (fr & 7)) * 16;
;     const int aoff = (16 * (w & 3) + fr) * 128;
;     ...
;     const int nmain = nchunk - PD;
; #pragma unroll 1
;     for (int c = 0; c < nmain; ++c) {
;         MR_ISSUE(c + PD);
;         asm volatile("s_waitcnt vmcnt(12)" ::: "memory"); __builtin_amdgcn_s_barrier(); asm volatile("" ::: "memory");
;         MR_CONSUME(c);
;     }
.LBB0_1468:
	s_add_i32 s17, s0, 0x18000
	s_mov_b32 m0, s17
	s_nop 0
	global_load_lds_dwordx4 v[6:7], off
	s_addk_i32 s17, 0x2000
	s_mov_b32 m0, s17
	s_nop 0
	global_load_lds_dwordx4 v[4:5], off
	v_lshl_add_u64 v[4:5], v[4:5], 0, s[38:39]
	v_lshl_add_u64 v[6:7], v[6:7], 0, s[38:39]
	v_cndmask_b32_e64 v0, 0, 1, s[12:13]
	v_cmp_ne_u32_e64 s[10:11], 1, v0
.Lmr_e_head:
	s_waitcnt vmcnt(12)
	s_barrier
	s_andn2_b64 vcc, exec, s[12:13]
	s_cbranch_vccnz .Lmr_e_issue
	s_and_b32 s17, s1, 0x1c000
	v_add_u32_e32 v0, s17, v12
	v_add_u32_e32 v2, v0, v9
	v_add_u32_e32 v3, s17, v11
	v_add_u32_e32 v13, v3, v9
	v_add_u32_e32 v0, v0, v10
	v_add_u32_e32 v3, v3, v10
	ds_read_b128 v[44:47], v13
	ds_read_b128 v[48:51], v2 offset:8192
	ds_read_b128 v[52:55], v2 offset:10240
	ds_read_b128 v[56:59], v2 offset:12288
	ds_read_b128 v[60:63], v2 offset:14336
	ds_read_b128 v[64:67], v3
	ds_read_b128 v[68:71], v0 offset:8192
	ds_read_b128 v[72:75], v0 offset:10240
	ds_read_b128 v[76:79], v0 offset:12288
	ds_read_b128 v[14:17], v0 offset:14336
.Lmr_e_issue:
	s_cmp_eq_u32 s1, 0x94000
	s_cbranch_scc1 .Lmr_e_nodma
	s_add_i32 s17, s1, 0x1c000
	s_and_b32 s17, s17, 0x1c000
	s_add_i32 s17, s17, s0
	s_mov_b32 m0, s17
	s_nop 0
	global_load_lds_dwordx4 v[6:7], off
	s_addk_i32 s17, 0x2000
	s_mov_b32 m0, s17
	s_nop 0
	global_load_lds_dwordx4 v[4:5], off
	v_lshl_add_u64 v[4:5], v[4:5], 0, s[38:39]
	v_lshl_add_u64 v[6:7], v[6:7], 0, s[38:39]
.Lmr_e_nodma:
	s_addk_i32 s1, 0x4000
	s_cbranch_vccnz .Lmr_e_tail
	s_waitcnt lgkmcnt(8)
	v_mfma_f32_16x16x32_bf16 v[30:33], v[48:51], v[44:47], v[30:33]
	s_waitcnt lgkmcnt(7)
	v_mfma_f32_16x16x32_bf16 v[34:37], v[52:55], v[44:47], v[34:37]
	s_waitcnt lgkmcnt(6)
	v_mfma_f32_16x16x32_bf16 v[18:21], v[56:59], v[44:47], v[18:21]
	s_waitcnt lgkmcnt(5)
	v_mfma_f32_16x16x32_bf16 v[22:25], v[60:63], v[44:47], v[22:25]
	s_waitcnt lgkmcnt(3)
	v_mfma_f32_16x16x32_bf16 v[30:33], v[68:71], v[64:67], v[30:33]
	s_waitcnt lgkmcnt(2)
	v_mfma_f32_16x16x32_bf16 v[34:37], v[72:75], v[64:67], v[34:37]
	s_waitcnt lgkmcnt(1)
	v_mfma_f32_16x16x32_bf16 v[18:21], v[76:79], v[64:67], v[18:21]
	s_waitcnt lgkmcnt(0)
	v_mfma_f32_16x16x32_bf16 v[22:25], v[14:17], v[64:67], v[22:25]
.Lmr_e_tail:
	s_cmp_eq_u32 s1, 0x98000
	s_cbranch_scc0 .Lmr_e_head
